# mixer recurrence combine: removed false-dependency vmcnt(3) wait (pk_mul reads v[104:105] but only v104 via op_sel; v105 is a next-chunk load dest) so next-chunk loads overlap combine+barrier
# speedup vs baseline: 1.0064x; 1.0037x over previous
; __device__ __forceinline__ unsigned pk2(float lo, float hi) { return pg8::cvt_pk_bf16(lo, hi); }
; __device__ __forceinline__ float bf2f(unsigned b) { return __uint_as_float(b << 16); }
; #define WG_BAR() do { asm volatile("s_waitcnt lgkmcnt(0)" ::: "memory"); __builtin_amdgcn_s_barrier(); asm volatile("" ::: "memory"); } while (0)
; __device__ __forceinline__ void mixer_phase(LAS unsigned char* lds, const bf16_t* __restrict__ QKc, const bf16_t* __restrict__ PROJ, bf16_t* HOUT, const float* __restrict__ DEN, const float* __restrict__ GS, int vcu, int G) {
;     ...
;             { unpair16(opl, quad, op0, op1);
;               const float sit = vb[128 + tl], rf = vb[tl];
;               const float den = sit * __shfl(accO[2][0], l15) + rf * denp;
;               float inv = 1.0f; if (!grp) inv = 1.0f / fmaxf(fabsf(den), vb[256 + tl]);
;               const float o0[4] = {bf2f(op0.x & 0xffffu), bf2f(op0.x >> 16), bf2f(op0.y & 0xffffu), bf2f(op0.y >> 16)}, o1[4] = {bf2f(op1.x & 0xffffu), bf2f(op1.x >> 16), bf2f(op1.y & 0xffffu), bf2f(op1.y >> 16)};
;               float r0[4], r1[4];
; #pragma unroll
;               for (int j = 0; j < 4; ++j) { r0[j] = (sit * accO[0][j] + rf * o0[j]) * inv; r1[j] = (sit * accO[1][j] + rf * o1[j]) * inv; }
;               u32x2 X, Y; X.x = pk2(r0[0], r0[1]); X.y = pk2(r0[2], r0[3]); Y.x = pk2(r1[0], r1[1]); Y.y = pk2(r1[2], r1[3]);
;               u32x4 o; const int e0 = pair16(X, Y, quad, o); *(u32x4*)(hdst + (size_t)(row0 + tl) * DM + e0) = o; }
;             WG_BAR();
.LBB0_519:
	s_waitcnt vmcnt(20) lgkmcnt(2)
	v_cndmask_b32_e64 v158, v215, v49, s[14:15]
	v_cndmask_b32_e64 v49, v214, v48, s[14:15]
	v_lshlrev_b32_e32 v48, 16, v49
	v_and_b32_e32 v49, 0xffff0000, v49
	v_cndmask_b32_e64 v51, v51, v215, s[14:15]
	s_waitcnt lgkmcnt(0)
	v_cndmask_b32_e64 v159, v50, v214, s[14:15]
	v_mov_b32_e32 v50, v107
	v_pk_mul_f32 v[48:49], v[106:107], v[48:49] op_sel_hi:[0,1]
	v_pk_fma_f32 v[48:49], v[100:101], v[50:51], v[48:49] op_sel_hi:[1,0,1]
	v_lshlrev_b32_e32 v100, 16, v159
	v_and_b32_e32 v101, 0xffff0000, v159
	v_pk_mul_f32 v[100:101], v[106:107], v[100:101] op_sel_hi:[0,1]
	v_pk_fma_f32 v[96:97], v[96:97], v[50:51], v[100:101] op_sel_hi:[1,0,1]
	v_lshlrev_b32_e32 v100, 16, v158
	v_and_b32_e32 v101, 0xffff0000, v158
	v_pk_mul_f32 v[100:101], v[106:107], v[100:101] op_sel_hi:[0,1]
	v_pk_fma_f32 v[100:101], v[102:103], v[50:51], v[100:101] op_sel_hi:[1,0,1]
	v_lshlrev_b32_e32 v102, 16, v51
	v_and_b32_e32 v103, 0xffff0000, v51
	v_pk_mul_f32 v[102:103], v[106:107], v[102:103] op_sel_hi:[0,1]
	v_pk_fma_f32 v[50:51], v[98:99], v[50:51], v[102:103] op_sel_hi:[1,0,1]
	s_nop 0
	v_pk_mul_f32 v[48:49], v[48:49], v[104:105] op_sel_hi:[1,0]
	v_pk_mul_f32 v[100:101], v[100:101], v[104:105] op_sel_hi:[1,0]
	v_pk_mul_f32 v[50:51], v[50:51], v[104:105] op_sel_hi:[1,0]
	v_pk_mul_f32 v[96:97], v[96:97], v[104:105] op_sel_hi:[1,0]
	v_cvt_pk_bf16_f32 v48, v48, v49
	v_cvt_pk_bf16_f32 v49, v100, v101
	v_cvt_pk_bf16_f32 v50, v50, v51
	v_cvt_pk_bf16_f32 v96, v96, v97
	v_cndmask_b32_e64 v51, v49, v50, s[14:15]
	ds_bpermute_b32 v97, v212, v51
	v_cndmask_b32_e64 v51, v48, v96, s[14:15]
	ds_bpermute_b32 v98, v212, v51
	s_add_u32 s86, s86, 0x640
	s_mov_b64 s[50:51], 0x80000
	s_waitcnt lgkmcnt(1)
	v_cndmask_b32_e64 v51, v50, v97, s[14:15]
	v_cndmask_b32_e64 v49, v97, v49, s[14:15]
	s_waitcnt lgkmcnt(0)
	v_cndmask_b32_e64 v50, v96, v98, s[14:15]
	v_cndmask_b32_e64 v48, v98, v48, s[14:15]
	global_store_dwordx4 v[156:157], v[48:51], off
	s_waitcnt lgkmcnt(0)
	s_barrier
	s_addc_u32 s87, s87, 0
	s_add_i32 s85, s85, 1
	s_add_i32 s88, s88, 4
	v_lshl_add_u64 v[146:147], v[146:147], 0, s[34:35]
	v_lshl_add_u64 v[148:149], v[148:149], 0, s[50:51]
	v_lshl_add_u64 v[144:145], v[144:145], 0, s[36:37]
	v_lshl_add_u64 v[150:151], v[150:151], 0, s[38:39]
	v_lshl_add_u64 v[152:153], v[152:153], 0, s[40:41]
	s_cmp_eq_u32 s85, 32
	v_lshl_add_u64 v[154:155], v[154:155], 0, s[40:41]
	s_cbranch_scc1 .LBB0_531
